# phase_final: the four residual chunk loads and four K-split partial loads issued together, one wait (was load+wait per chunk)
# baseline (speedup 1.0000x reference)
.LBB0_942:
	v_add_u32_e32 v16, 0xffffc000, v42
	v_cmp_lt_i32_e32 vcc, s4, v42
	v_lshlrev_b64 v[24:25], 11, v[16:17]
	s_and_b64 s[14:15], s[0:1], vcc
	v_lshl_add_u64 v[40:41], v[18:19], 0, v[24:25]
	global_load_dwordx2 v[50:51], v[20:21], off offset:-1024 nt
	global_load_dwordx2 v[52:53], v[20:21], off offset:-512 nt
	global_load_dwordx2 v[54:55], v[20:21], off nt
	global_load_dwordx2 v[56:57], v[20:21], off offset:512 nt
	s_and_saveexec_b64 s[16:17], s[14:15]
	s_cbranch_execz .Lfin_nopart
	global_load_dwordx2 v[58:59], v[40:41], off
	global_load_dwordx2 v[60:61], v[40:41], off offset:512
	global_load_dwordx2 v[62:63], v[40:41], off offset:1024
	global_load_dwordx2 v[64:65], v[40:41], off offset:1536
.Lfin_nopart:
	s_or_b64 exec, exec, s[16:17]
	s_waitcnt vmcnt(0)
	v_lshlrev_b32_e32 v24, 16, v50
	v_and_b32_e32 v25, 0xffff0000, v50
	v_lshlrev_b32_e32 v26, 16, v51
	v_and_b32_e32 v27, 0xffff0000, v51
	v_lshlrev_b32_e32 v28, 16, v52
	v_and_b32_e32 v29, 0xffff0000, v52
	v_lshlrev_b32_e32 v30, 16, v53
	v_and_b32_e32 v31, 0xffff0000, v53
	v_lshlrev_b32_e32 v32, 16, v54
	v_and_b32_e32 v33, 0xffff0000, v54
	v_lshlrev_b32_e32 v34, 16, v55
	v_and_b32_e32 v35, 0xffff0000, v55
	v_lshlrev_b32_e32 v36, 16, v56
	v_and_b32_e32 v37, 0xffff0000, v56
	v_lshlrev_b32_e32 v38, 16, v57
	v_and_b32_e32 v39, 0xffff0000, v57
	s_and_saveexec_b64 s[16:17], s[14:15]
	s_cbranch_execz .LBB0_941
	v_lshlrev_b32_e32 v66, 16, v58
	v_and_b32_e32 v67, 0xffff0000, v58
	v_lshlrev_b32_e32 v68, 16, v59
	v_and_b32_e32 v69, 0xffff0000, v59
	v_pk_add_f32 v[26:27], v[26:27], v[68:69]
	v_pk_add_f32 v[24:25], v[24:25], v[66:67]
	s_nop 0
	v_cvt_pk_bf16_f32 v16, v24, v25
	v_cvt_pk_bf16_f32 v27, v26, v27
	s_nop 0
	v_lshlrev_b32_e32 v24, 16, v16
	v_and_b32_e32 v25, 0xffff0000, v16
	v_lshlrev_b32_e32 v26, 16, v27
	v_and_b32_e32 v27, 0xffff0000, v27
	v_lshlrev_b32_e32 v66, 16, v60
	v_and_b32_e32 v67, 0xffff0000, v60
	v_lshlrev_b32_e32 v68, 16, v61
	v_and_b32_e32 v69, 0xffff0000, v61
	v_pk_add_f32 v[30:31], v[30:31], v[68:69]
	v_pk_add_f32 v[28:29], v[28:29], v[66:67]
	s_nop 0
	v_cvt_pk_bf16_f32 v16, v28, v29
	v_cvt_pk_bf16_f32 v31, v30, v31
	s_nop 0
	v_lshlrev_b32_e32 v28, 16, v16
	v_and_b32_e32 v29, 0xffff0000, v16
	v_lshlrev_b32_e32 v30, 16, v31
	v_and_b32_e32 v31, 0xffff0000, v31
	v_lshlrev_b32_e32 v66, 16, v62
	v_and_b32_e32 v67, 0xffff0000, v62
	v_lshlrev_b32_e32 v68, 16, v63
	v_and_b32_e32 v69, 0xffff0000, v63
	v_pk_add_f32 v[34:35], v[34:35], v[68:69]
	v_pk_add_f32 v[32:33], v[32:33], v[66:67]
	s_nop 0
	v_cvt_pk_bf16_f32 v16, v32, v33
	v_cvt_pk_bf16_f32 v35, v34, v35
	s_nop 0
	v_lshlrev_b32_e32 v32, 16, v16
	v_and_b32_e32 v33, 0xffff0000, v16
	v_lshlrev_b32_e32 v34, 16, v35
	v_and_b32_e32 v35, 0xffff0000, v35
	v_lshlrev_b32_e32 v66, 16, v64
	v_and_b32_e32 v67, 0xffff0000, v64
	v_lshlrev_b32_e32 v68, 16, v65
	v_and_b32_e32 v69, 0xffff0000, v65
	v_pk_add_f32 v[38:39], v[38:39], v[68:69]
	v_pk_add_f32 v[36:37], v[36:37], v[66:67]
	s_nop 0
	v_cvt_pk_bf16_f32 v16, v36, v37
	v_cvt_pk_bf16_f32 v39, v38, v39
	s_nop 0
	v_lshlrev_b32_e32 v36, 16, v16
	v_and_b32_e32 v37, 0xffff0000, v16
	v_lshlrev_b32_e32 v38, 16, v39
	v_and_b32_e32 v39, 0xffff0000, v39
	s_branch .LBB0_941
